# P5 EpiRes epilogue: x loads batched per 128-row half
# speedup vs baseline: 1.0128x; 1.0019x over previous
; __device__ __forceinline__ u32x4 pack8(f32x4 a, f32x4 b) { u32x4 w; w.x = cvt_pk(a[0], a[1]); w.y = cvt_pk(a[2], a[3]); w.z = cvt_pk(b[0], b[1]); w.w = cvt_pk(b[2], b[3]); return w; }
;     __device__ __forceinline__ void operator()(EPI_ARGS) const {
;         const int row0 = u.pm * 256 + wr * 64 + fr, colt = u.pn * 256 + wc * 32 + 8 * fq;
; #pragma unroll
;         for (int ai = 0; ai < 2; ++ai)
; #pragma unroll
;             for (int m = 0; m < 4; ++m) { const int row = row0 + ai * 128 + m * 16; const size_t ro = (size_t)row * DM + colt; float s = 0.f;
; #pragma unroll
;                 for (int bj = 0; bj < 2; ++bj) { const size_t o = ro + bj * 128;
;                     f32x4 v0 = acc[ai][bj][m][0], v1 = acc[ai][bj][m][1];
;                     if (IN_BF16) { const u32x4 t = *(const u32x4*)((const bf16_t*)xin + o);
;                         v0[0] += bflo(t.x); v0[1] += bfhi(t.x); v0[2] += bflo(t.y); v0[3] += bfhi(t.y); v1[0] += bflo(t.z); v1[1] += bfhi(t.z); v1[2] += bflo(t.w); v1[3] += bfhi(t.w);
;                     } else { v0 = v0 + *(const f32x4*)((const float*)xin + o); v1 = v1 + *(const f32x4*)((const float*)xin + o + 4); }
;                     *(u32x4*)(xb + o) = pack8(v0, v1);
;                     s += ((v0[0] * v0[0] + v0[1] * v0[1]) + (v0[2] * v0[2] + v0[3] * v0[3])) + ((v1[0] * v1[0] + v1[1] * v1[1]) + (v1[2] * v1[2] + v1[3] * v1[3])); }
.LBB0_795:
	s_lshl_b32 s15, s35, 8
	s_or_b32 s15, s15, s43
	v_ashrrev_i32_e32 v140, 1, v144
	v_and_b32_e32 v140, -8, v140
	v_add_u32_e32 v140, s15, v140
	v_and_or_b32 v141, v144, 15, s42
	v_lshl_add_u32 v142, s6, 8, v141
	v_lshlrev_b32_e32 v222, 12, v142
	v_lshl_add_u32 v222, v140, 2, v222
	v_lshlrev_b32_e32 v223, 11, v142
	v_lshl_add_u32 v223, v140, 1, v223
	s_lshl_b32 s15, s35, 4
	s_lshl_b32 s24, s41, 2
	s_add_i32 s15, s15, s24
	v_lshl_add_u32 v224, v142, 6, s15
	v_xor_b32_e32 v225, 16, v144
	v_lshlrev_b32_e32 v225, 2, v225
	v_xor_b32_e32 v226, 32, v144
	v_lshlrev_b32_e32 v226, 2, v226
	v_cmp_gt_u32_e32 vcc, 16, v144
	s_mov_b64 s[98:99], s[76:77]
	s_mov_b64 s[100:101], s[72:73]
	s_mov_b64 s[24:25], s[2:3]
	global_load_dwordx4 v[150:153], v222, s[98:99]
	global_load_dwordx4 v[154:157], v222, s[98:99] offset:16
	global_load_dwordx4 v[158:161], v222, s[98:99] offset:512
	global_load_dwordx4 v[162:165], v222, s[98:99] offset:528
	s_add_u32 s98, s98, 0x10000
	s_addc_u32 s99, s99, 0
	global_load_dwordx4 v[166:169], v222, s[98:99]
	global_load_dwordx4 v[170:173], v222, s[98:99] offset:16
	global_load_dwordx4 v[174:177], v222, s[98:99] offset:512
	global_load_dwordx4 v[178:181], v222, s[98:99] offset:528
	s_add_u32 s98, s98, 0x10000
	s_addc_u32 s99, s99, 0
	global_load_dwordx4 v[186:189], v222, s[98:99]
	global_load_dwordx4 v[190:193], v222, s[98:99] offset:16
	global_load_dwordx4 v[194:197], v222, s[98:99] offset:512
	global_load_dwordx4 v[198:201], v222, s[98:99] offset:528
	s_add_u32 s98, s98, 0x10000
	s_addc_u32 s99, s99, 0
	global_load_dwordx4 v[202:205], v222, s[98:99]
	global_load_dwordx4 v[206:209], v222, s[98:99] offset:16
	global_load_dwordx4 v[210:213], v222, s[98:99] offset:512
	global_load_dwordx4 v[238:241], v222, s[98:99] offset:528
	s_add_u32 s98, s98, 0x50000
	s_addc_u32 s99, s99, 0
	s_waitcnt vmcnt(0)
	v_pk_add_f32 v[124:125], v[124:125], v[150:151]
	v_pk_add_f32 v[126:127], v[126:127], v[152:153]
	v_pk_add_f32 v[120:121], v[120:121], v[154:155]
	v_pk_add_f32 v[122:123], v[122:123], v[156:157]
	v_pk_add_f32 v[116:117], v[116:117], v[158:159]
	v_pk_add_f32 v[118:119], v[118:119], v[160:161]
	v_pk_add_f32 v[112:113], v[112:113], v[162:163]
	v_pk_add_f32 v[114:115], v[114:115], v[164:165]
	v_pk_add_f32 v[108:109], v[108:109], v[166:167]
	v_pk_add_f32 v[110:111], v[110:111], v[168:169]
	v_pk_add_f32 v[104:105], v[104:105], v[170:171]
	v_pk_add_f32 v[106:107], v[106:107], v[172:173]
	v_pk_add_f32 v[100:101], v[100:101], v[174:175]
	v_pk_add_f32 v[102:103], v[102:103], v[176:177]
	v_pk_add_f32 v[96:97], v[96:97], v[178:179]
	v_pk_add_f32 v[98:99], v[98:99], v[180:181]
	v_pk_add_f32 v[92:93], v[92:93], v[186:187]
	v_pk_add_f32 v[94:95], v[94:95], v[188:189]
	v_pk_add_f32 v[88:89], v[88:89], v[190:191]
	v_pk_add_f32 v[90:91], v[90:91], v[192:193]
	v_pk_add_f32 v[84:85], v[84:85], v[194:195]
	v_pk_add_f32 v[86:87], v[86:87], v[196:197]
	v_pk_add_f32 v[80:81], v[80:81], v[198:199]
	v_pk_add_f32 v[82:83], v[82:83], v[200:201]
	v_pk_add_f32 v[76:77], v[76:77], v[202:203]
	v_pk_add_f32 v[78:79], v[78:79], v[204:205]
	v_pk_add_f32 v[72:73], v[72:73], v[206:207]
	v_pk_add_f32 v[74:75], v[74:75], v[208:209]
	v_pk_add_f32 v[68:69], v[68:69], v[210:211]
	v_pk_add_f32 v[70:71], v[70:71], v[212:213]
	v_pk_add_f32 v[64:65], v[64:65], v[238:239]
	v_pk_add_f32 v[66:67], v[66:67], v[240:241]
	global_load_dwordx4 v[150:153], v222, s[98:99]
	global_load_dwordx4 v[154:157], v222, s[98:99] offset:16
	global_load_dwordx4 v[158:161], v222, s[98:99] offset:512
	global_load_dwordx4 v[162:165], v222, s[98:99] offset:528
	s_add_u32 s98, s98, 0x10000
	s_addc_u32 s99, s99, 0
	global_load_dwordx4 v[166:169], v222, s[98:99]
	global_load_dwordx4 v[170:173], v222, s[98:99] offset:16
	global_load_dwordx4 v[174:177], v222, s[98:99] offset:512
	global_load_dwordx4 v[178:181], v222, s[98:99] offset:528
	s_add_u32 s98, s98, 0x10000
	s_addc_u32 s99, s99, 0
	global_load_dwordx4 v[186:189], v222, s[98:99]
	global_load_dwordx4 v[190:193], v222, s[98:99] offset:16
	global_load_dwordx4 v[194:197], v222, s[98:99] offset:512
	global_load_dwordx4 v[198:201], v222, s[98:99] offset:528
	s_add_u32 s98, s98, 0x10000
	s_addc_u32 s99, s99, 0
	global_load_dwordx4 v[202:205], v222, s[98:99]
	global_load_dwordx4 v[206:209], v222, s[98:99] offset:16
	global_load_dwordx4 v[210:213], v222, s[98:99] offset:512
	global_load_dwordx4 v[238:241], v222, s[98:99] offset:528
	s_add_u32 s98, s98, 0x50000
	s_addc_u32 s99, s99, 0
	v_mul_f32_e32 v242, v125, v125
	v_mul_f32_e32 v243, v127, v127
	v_mul_f32_e32 v244, v121, v121
	v_mul_f32_e32 v245, v123, v123
	v_fmac_f32_e32 v242, v124, v124
	v_fmac_f32_e32 v243, v126, v126
	v_fmac_f32_e32 v244, v120, v120
	v_fmac_f32_e32 v245, v122, v122
	v_add_f32_e32 v242, v242, v243
	v_add_f32_e32 v243, v244, v245
	v_add_f32_e32 v227, v242, v243
	v_cvt_pk_bf16_f32 v230, v124, v125
	v_cvt_pk_bf16_f32 v231, v126, v127
	v_cvt_pk_bf16_f32 v232, v120, v121
	v_cvt_pk_bf16_f32 v233, v122, v123
	global_store_dwordx4 v223, v[230:233], s[100:101]
	v_mul_f32_e32 v242, v117, v117
	v_mul_f32_e32 v243, v119, v119
	v_mul_f32_e32 v244, v113, v113
	v_mul_f32_e32 v245, v115, v115
	v_fmac_f32_e32 v242, v116, v116
	v_fmac_f32_e32 v243, v118, v118
	v_fmac_f32_e32 v244, v112, v112
	v_fmac_f32_e32 v245, v114, v114
	v_add_f32_e32 v242, v242, v243
	v_add_f32_e32 v243, v244, v245
	v_add_f32_e32 v228, v242, v243
	v_cvt_pk_bf16_f32 v234, v116, v117
	v_cvt_pk_bf16_f32 v235, v118, v119
	v_cvt_pk_bf16_f32 v236, v112, v113
	v_cvt_pk_bf16_f32 v237, v114, v115
	global_store_dwordx4 v223, v[234:237], s[100:101] offset:256
	v_add_f32_e32 v227, v227, v228
	ds_bpermute_b32 v228, v225, v227
	s_waitcnt lgkmcnt(0)
; __device__ __forceinline__ u32x4 pack8(f32x4 a, f32x4 b) { u32x4 w; w.x = cvt_pk(a[0], a[1]); w.y = cvt_pk(a[2], a[3]); w.z = cvt_pk(b[0], b[1]); w.w = cvt_pk(b[2], b[3]); return w; }
;     __device__ __forceinline__ void operator()(EPI_ARGS) const {
;     ...
;             for (int m = 0; m < 4; ++m) { const int row = row0 + ai * 128 + m * 16; const size_t ro = (size_t)row * DM + colt; float s = 0.f;
; #pragma unroll
;                 for (int bj = 0; bj < 2; ++bj) { const size_t o = ro + bj * 128;
;                     f32x4 v0 = acc[ai][bj][m][0], v1 = acc[ai][bj][m][1];
;                     if (IN_BF16) { const u32x4 t = *(const u32x4*)((const bf16_t*)xin + o);
;                         v0[0] += bflo(t.x); v0[1] += bfhi(t.x); v0[2] += bflo(t.y); v0[3] += bfhi(t.y); v1[0] += bflo(t.z); v1[1] += bfhi(t.z); v1[2] += bflo(t.w); v1[3] += bfhi(t.w);
;                     } else { v0 = v0 + *(const f32x4*)((const float*)xin + o); v1 = v1 + *(const f32x4*)((const float*)xin + o + 4); }
;                     *(u32x4*)(xb + o) = pack8(v0, v1);
;                     s += ((v0[0] * v0[0] + v0[1] * v0[1]) + (v0[2] * v0[2] + v0[3] * v0[3])) + ((v1[0] * v1[0] + v1[1] * v1[1]) + (v1[2] * v1[2] + v1[3] * v1[3])); }
;                 s += __shfl_xor(s, 16); s += __shfl_xor(s, 32);
;                 if (fq == 0) ss[(size_t)row * 16 + u.pn * 4 + wc] = s; }
	v_add_f32_e32 v227, v227, v228
	ds_bpermute_b32 v228, v226, v227
	s_waitcnt lgkmcnt(0)
	v_add_f32_e32 v227, v227, v228
	s_and_saveexec_b64 s[22:23], vcc
	global_store_dword v224, v227, s[24:25]
	s_or_b64 exec, exec, s[22:23]
	s_add_u32 s100, s100, 0x8000
	s_addc_u32 s101, s101, 0
	s_add_u32 s24, s24, 0x400
	s_addc_u32 s25, s25, 0
	v_mul_f32_e32 v242, v109, v109
	v_mul_f32_e32 v243, v111, v111
	v_mul_f32_e32 v244, v105, v105
	v_mul_f32_e32 v245, v107, v107
	v_fmac_f32_e32 v242, v108, v108
	v_fmac_f32_e32 v243, v110, v110
	v_fmac_f32_e32 v244, v104, v104
	v_fmac_f32_e32 v245, v106, v106
	v_add_f32_e32 v242, v242, v243
	v_add_f32_e32 v243, v244, v245
	v_add_f32_e32 v227, v242, v243
	v_cvt_pk_bf16_f32 v230, v108, v109
	v_cvt_pk_bf16_f32 v231, v110, v111
	v_cvt_pk_bf16_f32 v232, v104, v105
	v_cvt_pk_bf16_f32 v233, v106, v107
	global_store_dwordx4 v223, v[230:233], s[100:101]
	v_mul_f32_e32 v242, v101, v101
	v_mul_f32_e32 v243, v103, v103
	v_mul_f32_e32 v244, v97, v97
	v_mul_f32_e32 v245, v99, v99
	v_fmac_f32_e32 v242, v100, v100
	v_fmac_f32_e32 v243, v102, v102
	v_fmac_f32_e32 v244, v96, v96
	v_fmac_f32_e32 v245, v98, v98
	v_add_f32_e32 v242, v242, v243
	v_add_f32_e32 v243, v244, v245
	v_add_f32_e32 v228, v242, v243
	v_cvt_pk_bf16_f32 v234, v100, v101
	v_cvt_pk_bf16_f32 v235, v102, v103
	v_cvt_pk_bf16_f32 v236, v96, v97
	v_cvt_pk_bf16_f32 v237, v98, v99
	global_store_dwordx4 v223, v[234:237], s[100:101] offset:256
	v_add_f32_e32 v227, v227, v228
	ds_bpermute_b32 v228, v225, v227
	s_waitcnt lgkmcnt(0)
	v_add_f32_e32 v227, v227, v228
	ds_bpermute_b32 v228, v226, v227
	s_waitcnt lgkmcnt(0)
	v_add_f32_e32 v227, v227, v228
	s_and_saveexec_b64 s[22:23], vcc
	global_store_dword v224, v227, s[24:25]
	s_or_b64 exec, exec, s[22:23]
	s_add_u32 s100, s100, 0x8000
	s_addc_u32 s101, s101, 0
	s_add_u32 s24, s24, 0x400
	s_addc_u32 s25, s25, 0
	v_mul_f32_e32 v242, v93, v93
	v_mul_f32_e32 v243, v95, v95
	v_mul_f32_e32 v244, v89, v89
	v_mul_f32_e32 v245, v91, v91
	v_fmac_f32_e32 v242, v92, v92
	v_fmac_f32_e32 v243, v94, v94
	v_fmac_f32_e32 v244, v88, v88
	v_fmac_f32_e32 v245, v90, v90
	v_add_f32_e32 v242, v242, v243
	v_add_f32_e32 v243, v244, v245
	v_add_f32_e32 v227, v242, v243
	v_cvt_pk_bf16_f32 v230, v92, v93
	v_cvt_pk_bf16_f32 v231, v94, v95
	v_cvt_pk_bf16_f32 v232, v88, v89
	v_cvt_pk_bf16_f32 v233, v90, v91
	global_store_dwordx4 v223, v[230:233], s[100:101]
	v_mul_f32_e32 v242, v85, v85
	v_mul_f32_e32 v243, v87, v87
	v_mul_f32_e32 v244, v81, v81
	v_mul_f32_e32 v245, v83, v83
	v_fmac_f32_e32 v242, v84, v84
	v_fmac_f32_e32 v243, v86, v86
	v_fmac_f32_e32 v244, v80, v80
	v_fmac_f32_e32 v245, v82, v82
	v_add_f32_e32 v242, v242, v243
	v_add_f32_e32 v243, v244, v245
	v_add_f32_e32 v228, v242, v243
	v_cvt_pk_bf16_f32 v234, v84, v85
	v_cvt_pk_bf16_f32 v235, v86, v87
	v_cvt_pk_bf16_f32 v236, v80, v81
	v_cvt_pk_bf16_f32 v237, v82, v83
	global_store_dwordx4 v223, v[234:237], s[100:101] offset:256
	v_add_f32_e32 v227, v227, v228
	ds_bpermute_b32 v228, v225, v227
	s_waitcnt lgkmcnt(0)
	v_add_f32_e32 v227, v227, v228
	ds_bpermute_b32 v228, v226, v227
	s_waitcnt lgkmcnt(0)
	v_add_f32_e32 v227, v227, v228
	s_and_saveexec_b64 s[22:23], vcc
	global_store_dword v224, v227, s[24:25]
	s_or_b64 exec, exec, s[22:23]
	s_add_u32 s100, s100, 0x8000
	s_addc_u32 s101, s101, 0
	s_add_u32 s24, s24, 0x400
	s_addc_u32 s25, s25, 0
	v_mul_f32_e32 v242, v77, v77
	v_mul_f32_e32 v243, v79, v79
	v_mul_f32_e32 v244, v73, v73
	v_mul_f32_e32 v245, v75, v75
	v_fmac_f32_e32 v242, v76, v76
	v_fmac_f32_e32 v243, v78, v78
	v_fmac_f32_e32 v244, v72, v72
	v_fmac_f32_e32 v245, v74, v74
	v_add_f32_e32 v242, v242, v243
	v_add_f32_e32 v243, v244, v245
	v_add_f32_e32 v227, v242, v243
	v_cvt_pk_bf16_f32 v230, v76, v77
	v_cvt_pk_bf16_f32 v231, v78, v79
	v_cvt_pk_bf16_f32 v232, v72, v73
	v_cvt_pk_bf16_f32 v233, v74, v75
	global_store_dwordx4 v223, v[230:233], s[100:101]
	v_mul_f32_e32 v242, v69, v69
	v_mul_f32_e32 v243, v71, v71
	v_mul_f32_e32 v244, v65, v65
	v_mul_f32_e32 v245, v67, v67
	v_fmac_f32_e32 v242, v68, v68
	v_fmac_f32_e32 v243, v70, v70
	v_fmac_f32_e32 v244, v64, v64
	v_fmac_f32_e32 v245, v66, v66
	v_add_f32_e32 v242, v242, v243
	v_add_f32_e32 v243, v244, v245
	v_add_f32_e32 v228, v242, v243
	v_cvt_pk_bf16_f32 v234, v68, v69
	v_cvt_pk_bf16_f32 v235, v70, v71
	v_cvt_pk_bf16_f32 v236, v64, v65
	v_cvt_pk_bf16_f32 v237, v66, v67
	global_store_dwordx4 v223, v[234:237], s[100:101] offset:256
	v_add_f32_e32 v227, v227, v228
	ds_bpermute_b32 v228, v225, v227
	s_waitcnt lgkmcnt(0)
	v_add_f32_e32 v227, v227, v228
	ds_bpermute_b32 v228, v226, v227
	s_waitcnt lgkmcnt(0)
	v_add_f32_e32 v227, v227, v228
	s_and_saveexec_b64 s[22:23], vcc
	global_store_dword v224, v227, s[24:25]
	s_or_b64 exec, exec, s[22:23]
	s_add_u32 s100, s100, 0x28000
	s_addc_u32 s101, s101, 0
	s_add_u32 s24, s24, 0x1400
	s_addc_u32 s25, s25, 0
	s_waitcnt vmcnt(12)
; __device__ __forceinline__ u32x4 pack8(f32x4 a, f32x4 b) { u32x4 w; w.x = cvt_pk(a[0], a[1]); w.y = cvt_pk(a[2], a[3]); w.z = cvt_pk(b[0], b[1]); w.w = cvt_pk(b[2], b[3]); return w; }
;     __device__ __forceinline__ void operator()(EPI_ARGS) const {
;     ...
;                     f32x4 v0 = acc[ai][bj][m][0], v1 = acc[ai][bj][m][1];
;                     if (IN_BF16) { const u32x4 t = *(const u32x4*)((const bf16_t*)xin + o);
;                         v0[0] += bflo(t.x); v0[1] += bfhi(t.x); v0[2] += bflo(t.y); v0[3] += bfhi(t.y); v1[0] += bflo(t.z); v1[1] += bfhi(t.z); v1[2] += bflo(t.w); v1[3] += bfhi(t.w);
;                     } else { v0 = v0 + *(const f32x4*)((const float*)xin + o); v1 = v1 + *(const f32x4*)((const float*)xin + o + 4); }
;                     *(u32x4*)(xb + o) = pack8(v0, v1);
;                     s += ((v0[0] * v0[0] + v0[1] * v0[1]) + (v0[2] * v0[2] + v0[3] * v0[3])) + ((v1[0] * v1[0] + v1[1] * v1[1]) + (v1[2] * v1[2] + v1[3] * v1[3])); }
;                 s += __shfl_xor(s, 16); s += __shfl_xor(s, 32);
;                 if (fq == 0) ss[(size_t)row * 16 + u.pn * 4 + wc] = s; }
	v_pk_add_f32 v[60:61], v[60:61], v[150:151]
	v_pk_add_f32 v[62:63], v[62:63], v[152:153]
	v_pk_add_f32 v[56:57], v[56:57], v[154:155]
	v_pk_add_f32 v[58:59], v[58:59], v[156:157]
	v_pk_add_f32 v[52:53], v[52:53], v[158:159]
	v_pk_add_f32 v[54:55], v[54:55], v[160:161]
	v_pk_add_f32 v[48:49], v[48:49], v[162:163]
	v_pk_add_f32 v[50:51], v[50:51], v[164:165]
	v_pk_add_f32 v[44:45], v[44:45], v[166:167]
	v_pk_add_f32 v[46:47], v[46:47], v[168:169]
	v_pk_add_f32 v[40:41], v[40:41], v[170:171]
	v_pk_add_f32 v[42:43], v[42:43], v[172:173]
	v_pk_add_f32 v[36:37], v[36:37], v[174:175]
	v_pk_add_f32 v[38:39], v[38:39], v[176:177]
	v_pk_add_f32 v[32:33], v[32:33], v[178:179]
	v_pk_add_f32 v[34:35], v[34:35], v[180:181]
	v_pk_add_f32 v[28:29], v[28:29], v[186:187]
	v_pk_add_f32 v[30:31], v[30:31], v[188:189]
	v_pk_add_f32 v[24:25], v[24:25], v[190:191]
	v_pk_add_f32 v[26:27], v[26:27], v[192:193]
	v_pk_add_f32 v[20:21], v[20:21], v[194:195]
	v_pk_add_f32 v[22:23], v[22:23], v[196:197]
	v_pk_add_f32 v[16:17], v[16:17], v[198:199]
	v_pk_add_f32 v[18:19], v[18:19], v[200:201]
	v_pk_add_f32 v[12:13], v[12:13], v[202:203]
	v_pk_add_f32 v[14:15], v[14:15], v[204:205]
	v_pk_add_f32 v[8:9], v[8:9], v[206:207]
	v_pk_add_f32 v[10:11], v[10:11], v[208:209]
	v_pk_add_f32 v[4:5], v[4:5], v[210:211]
	v_pk_add_f32 v[6:7], v[6:7], v[212:213]
	v_pk_add_f32 v[0:1], v[0:1], v[238:239]
	v_pk_add_f32 v[2:3], v[2:3], v[240:241]
	v_mul_f32_e32 v242, v61, v61
	v_mul_f32_e32 v243, v63, v63
	v_mul_f32_e32 v244, v57, v57
	v_mul_f32_e32 v245, v59, v59
	v_fmac_f32_e32 v242, v60, v60
	v_fmac_f32_e32 v243, v62, v62
	v_fmac_f32_e32 v244, v56, v56
	v_fmac_f32_e32 v245, v58, v58
	v_add_f32_e32 v242, v242, v243
	v_add_f32_e32 v243, v244, v245
	v_add_f32_e32 v227, v242, v243
	v_cvt_pk_bf16_f32 v230, v60, v61
	v_cvt_pk_bf16_f32 v231, v62, v63
	v_cvt_pk_bf16_f32 v232, v56, v57
	v_cvt_pk_bf16_f32 v233, v58, v59
	global_store_dwordx4 v223, v[230:233], s[100:101]
	v_mul_f32_e32 v242, v53, v53
	v_mul_f32_e32 v243, v55, v55
	v_mul_f32_e32 v244, v49, v49
	v_mul_f32_e32 v245, v51, v51
	v_fmac_f32_e32 v242, v52, v52
	v_fmac_f32_e32 v243, v54, v54
	v_fmac_f32_e32 v244, v48, v48
	v_fmac_f32_e32 v245, v50, v50
	v_add_f32_e32 v242, v242, v243
	v_add_f32_e32 v243, v244, v245
	v_add_f32_e32 v228, v242, v243
	v_cvt_pk_bf16_f32 v234, v52, v53
	v_cvt_pk_bf16_f32 v235, v54, v55
	v_cvt_pk_bf16_f32 v236, v48, v49
	v_cvt_pk_bf16_f32 v237, v50, v51
	global_store_dwordx4 v223, v[234:237], s[100:101] offset:256
	v_add_f32_e32 v227, v227, v228
	ds_bpermute_b32 v228, v225, v227
	s_waitcnt lgkmcnt(0)
	v_add_f32_e32 v227, v227, v228
	ds_bpermute_b32 v228, v226, v227
	s_waitcnt lgkmcnt(0)
	v_add_f32_e32 v227, v227, v228
	s_and_saveexec_b64 s[22:23], vcc
	global_store_dword v224, v227, s[24:25]
	s_or_b64 exec, exec, s[22:23]
	s_add_u32 s100, s100, 0x8000
	s_addc_u32 s101, s101, 0
	s_add_u32 s24, s24, 0x400
	s_addc_u32 s25, s25, 0
	v_mul_f32_e32 v242, v45, v45
	v_mul_f32_e32 v243, v47, v47
	v_mul_f32_e32 v244, v41, v41
	v_mul_f32_e32 v245, v43, v43
	v_fmac_f32_e32 v242, v44, v44
	v_fmac_f32_e32 v243, v46, v46
	v_fmac_f32_e32 v244, v40, v40
	v_fmac_f32_e32 v245, v42, v42
	v_add_f32_e32 v242, v242, v243
	v_add_f32_e32 v243, v244, v245
	v_add_f32_e32 v227, v242, v243
	v_cvt_pk_bf16_f32 v230, v44, v45
	v_cvt_pk_bf16_f32 v231, v46, v47
	v_cvt_pk_bf16_f32 v232, v40, v41
	v_cvt_pk_bf16_f32 v233, v42, v43
	global_store_dwordx4 v223, v[230:233], s[100:101]
	v_mul_f32_e32 v242, v37, v37
	v_mul_f32_e32 v243, v39, v39
	v_mul_f32_e32 v244, v33, v33
	v_mul_f32_e32 v245, v35, v35
	v_fmac_f32_e32 v242, v36, v36
	v_fmac_f32_e32 v243, v38, v38
	v_fmac_f32_e32 v244, v32, v32
	v_fmac_f32_e32 v245, v34, v34
	v_add_f32_e32 v242, v242, v243
	v_add_f32_e32 v243, v244, v245
	v_add_f32_e32 v228, v242, v243
	v_cvt_pk_bf16_f32 v234, v36, v37
	v_cvt_pk_bf16_f32 v235, v38, v39
	v_cvt_pk_bf16_f32 v236, v32, v33
	v_cvt_pk_bf16_f32 v237, v34, v35
	global_store_dwordx4 v223, v[234:237], s[100:101] offset:256
	v_add_f32_e32 v227, v227, v228
	ds_bpermute_b32 v228, v225, v227
	s_waitcnt lgkmcnt(0)
; __device__ __forceinline__ u32x4 pack8(f32x4 a, f32x4 b) { u32x4 w; w.x = cvt_pk(a[0], a[1]); w.y = cvt_pk(a[2], a[3]); w.z = cvt_pk(b[0], b[1]); w.w = cvt_pk(b[2], b[3]); return w; }
;     __device__ __forceinline__ void operator()(EPI_ARGS) const {
;     ...
;             for (int m = 0; m < 4; ++m) { const int row = row0 + ai * 128 + m * 16; const size_t ro = (size_t)row * DM + colt; float s = 0.f;
; #pragma unroll
;                 for (int bj = 0; bj < 2; ++bj) { const size_t o = ro + bj * 128;
;                     f32x4 v0 = acc[ai][bj][m][0], v1 = acc[ai][bj][m][1];
;                     if (IN_BF16) { const u32x4 t = *(const u32x4*)((const bf16_t*)xin + o);
;                         v0[0] += bflo(t.x); v0[1] += bfhi(t.x); v0[2] += bflo(t.y); v0[3] += bfhi(t.y); v1[0] += bflo(t.z); v1[1] += bfhi(t.z); v1[2] += bflo(t.w); v1[3] += bfhi(t.w);
;                     } else { v0 = v0 + *(const f32x4*)((const float*)xin + o); v1 = v1 + *(const f32x4*)((const float*)xin + o + 4); }
;                     *(u32x4*)(xb + o) = pack8(v0, v1);
;                     s += ((v0[0] * v0[0] + v0[1] * v0[1]) + (v0[2] * v0[2] + v0[3] * v0[3])) + ((v1[0] * v1[0] + v1[1] * v1[1]) + (v1[2] * v1[2] + v1[3] * v1[3])); }
;                 s += __shfl_xor(s, 16); s += __shfl_xor(s, 32);
;                 if (fq == 0) ss[(size_t)row * 16 + u.pn * 4 + wc] = s; }
	v_add_f32_e32 v227, v227, v228
	ds_bpermute_b32 v228, v226, v227
	s_waitcnt lgkmcnt(0)
	v_add_f32_e32 v227, v227, v228
	s_and_saveexec_b64 s[22:23], vcc
	global_store_dword v224, v227, s[24:25]
	s_or_b64 exec, exec, s[22:23]
	s_add_u32 s100, s100, 0x8000
	s_addc_u32 s101, s101, 0
	s_add_u32 s24, s24, 0x400
	s_addc_u32 s25, s25, 0
	v_mul_f32_e32 v242, v29, v29
	v_mul_f32_e32 v243, v31, v31
	v_mul_f32_e32 v244, v25, v25
	v_mul_f32_e32 v245, v27, v27
	v_fmac_f32_e32 v242, v28, v28
	v_fmac_f32_e32 v243, v30, v30
	v_fmac_f32_e32 v244, v24, v24
	v_fmac_f32_e32 v245, v26, v26
	v_add_f32_e32 v242, v242, v243
	v_add_f32_e32 v243, v244, v245
	v_add_f32_e32 v227, v242, v243
	v_cvt_pk_bf16_f32 v230, v28, v29
	v_cvt_pk_bf16_f32 v231, v30, v31
	v_cvt_pk_bf16_f32 v232, v24, v25
	v_cvt_pk_bf16_f32 v233, v26, v27
	global_store_dwordx4 v223, v[230:233], s[100:101]
	v_mul_f32_e32 v242, v21, v21
	v_mul_f32_e32 v243, v23, v23
	v_mul_f32_e32 v244, v17, v17
	v_mul_f32_e32 v245, v19, v19
	v_fmac_f32_e32 v242, v20, v20
	v_fmac_f32_e32 v243, v22, v22
	v_fmac_f32_e32 v244, v16, v16
	v_fmac_f32_e32 v245, v18, v18
	v_add_f32_e32 v242, v242, v243
	v_add_f32_e32 v243, v244, v245
	v_add_f32_e32 v228, v242, v243
	v_cvt_pk_bf16_f32 v234, v20, v21
	v_cvt_pk_bf16_f32 v235, v22, v23
	v_cvt_pk_bf16_f32 v236, v16, v17
	v_cvt_pk_bf16_f32 v237, v18, v19
	global_store_dwordx4 v223, v[234:237], s[100:101] offset:256
	v_add_f32_e32 v227, v227, v228
	ds_bpermute_b32 v228, v225, v227
	s_waitcnt lgkmcnt(0)
	v_add_f32_e32 v227, v227, v228
	ds_bpermute_b32 v228, v226, v227
	s_waitcnt lgkmcnt(0)
	v_add_f32_e32 v227, v227, v228
	s_and_saveexec_b64 s[22:23], vcc
	global_store_dword v224, v227, s[24:25]
	s_or_b64 exec, exec, s[22:23]
	s_add_u32 s100, s100, 0x8000
	s_addc_u32 s101, s101, 0
	s_add_u32 s24, s24, 0x400
	s_addc_u32 s25, s25, 0
	v_mul_f32_e32 v242, v13, v13
	v_mul_f32_e32 v243, v15, v15
	v_mul_f32_e32 v244, v9, v9
	v_mul_f32_e32 v245, v11, v11
	v_fmac_f32_e32 v242, v12, v12
	v_fmac_f32_e32 v243, v14, v14
	v_fmac_f32_e32 v244, v8, v8
	v_fmac_f32_e32 v245, v10, v10
	v_add_f32_e32 v242, v242, v243
	v_add_f32_e32 v243, v244, v245
	v_add_f32_e32 v227, v242, v243
	v_cvt_pk_bf16_f32 v230, v12, v13
	v_cvt_pk_bf16_f32 v231, v14, v15
	v_cvt_pk_bf16_f32 v232, v8, v9
	v_cvt_pk_bf16_f32 v233, v10, v11
	global_store_dwordx4 v223, v[230:233], s[100:101]
	v_mul_f32_e32 v242, v5, v5
	v_mul_f32_e32 v243, v7, v7
	v_mul_f32_e32 v244, v1, v1
	v_mul_f32_e32 v245, v3, v3
	v_fmac_f32_e32 v242, v4, v4
	v_fmac_f32_e32 v243, v6, v6
	v_fmac_f32_e32 v244, v0, v0
	v_fmac_f32_e32 v245, v2, v2
	v_add_f32_e32 v242, v242, v243
	v_add_f32_e32 v243, v244, v245
	v_add_f32_e32 v228, v242, v243
	v_cvt_pk_bf16_f32 v234, v4, v5
	v_cvt_pk_bf16_f32 v235, v6, v7
	v_cvt_pk_bf16_f32 v236, v0, v1
	v_cvt_pk_bf16_f32 v237, v2, v3
	global_store_dwordx4 v223, v[234:237], s[100:101] offset:256
	v_add_f32_e32 v227, v227, v228
	ds_bpermute_b32 v228, v225, v227
	s_waitcnt lgkmcnt(0)
	v_add_f32_e32 v227, v227, v228
	ds_bpermute_b32 v228, v226, v227
	s_waitcnt lgkmcnt(0)
	v_add_f32_e32 v227, v227, v228
	s_and_saveexec_b64 s[22:23], vcc
	global_store_dword v224, v227, s[24:25]
	s_or_b64 exec, exec, s[22:23]
	s_add_u32 s100, s100, 0x28000
	s_addc_u32 s101, s101, 0
	s_add_u32 s24, s24, 0x1400
	s_addc_u32 s25, s25, 0
	s_andn2_b64 vcc, exec, s[16:17]
	s_mov_b64 s[16:17], -1
	s_cbranch_vccnz .LBB0_784
	s_andn2_b64 vcc, exec, s[8:9]
	s_cbranch_vccnz .LBB0_783
	s_barrier
	s_branch .LBB0_783
